# speedup vs baseline: 1.0007x; 1.0007x over previous
; DI_ void ssm_conv_tile(int tile, const unsigned char* buf, unsigned char* obuf, const float* cw, const float* cbias, bf16_t* xsT, bf16_t* Btok, bf16_t* BT, bf16_t* Ctok, int tid) {
;     ...
;     if (chmaj) { bf16_t* dst = (ch0 < 2048) ? xsT + (size_t)ch0 * XP : BT + (size_t)(ch0 - 2048) * XP;
; #pragma unroll
;         for (int k = 0; k < 2; ++k) { const int row = (tid >> 4) + 32 * k, c16 = tid & 15; *(u32x4*)(dst + (size_t)row * XP + tb + c16 * 8) = *(const u32x4*)(obuf2 + row * 272 + c16 * 16); } }
.LBB0_576:
	s_ashr_i32 s21, s20, 31
	v_add_u32_e32 v38, v80, v81
	s_lshl_b64 s[4:5], s[20:21], 1
	ds_read_b128 v[50:53], v38 offset:49920
	ds_read_b128 v[230:233], v38 offset:58624
	s_add_u32 s4, s40, s4
	s_addc_u32 s5, s41, s5
	v_lshlrev_b32_e32 v36, 1, v30
	v_mov_b32_e32 v37, v48
	v_lshl_add_u64 v[36:37], s[4:5], 0, v[36:37]
	v_lshl_add_u64 v[46:47], v[36:37], 0, v[32:33]
	s_waitcnt lgkmcnt(1)
	global_store_dwordx4 v[46:47], v[50:53], off
	v_readlane_b32 s42, v254, 38
	v_readlane_b32 s40, v254, 40
	v_lshl_add_u64 v[36:37], v[36:37], 0, v[34:35]
	v_readlane_b32 s43, v254, 39
	v_readlane_b32 s41, v254, 41
	s_waitcnt lgkmcnt(0)
	global_store_dwordx4 v[36:37], v[230:233], off
	s_andn2_b64 vcc, exec, s[18:19]
	s_cbranch_vccnz .LBB0_571
